# k19 + XCD-local hand-off P11->P12: final norm rows owned by the XCD that produced them, barrier among that XCD's 32 workgroups (grid barrier kept as fallback)
# baseline (speedup 1.0000x reference)
.LBB0_3:
	s_or_b64 exec, exec, s[0:1]
	s_waitcnt lgkmcnt(0)
	s_barrier
	s_add_u32 s96, s14, 0x4000
	s_getreg_b32 s0, hwreg(HW_REG_XCC_ID, 0, 4)
	s_addc_u32 s97, s15, 0
	s_and_b32 s91, s0, 15
	v_cmp_eq_u32_e64 s[4:5], 0, v0
	s_mov_b64 s[0:1], exec
	s_nop 0
	v_writelane_b32 v222, s4, 3
	s_nop 1
	v_writelane_b32 v222, s5, 4
	s_and_b64 s[4:5], s[0:1], s[4:5]
	s_mov_b64 exec, s[4:5]
	s_cbranch_execz .LBB0_6
	s_mov_b64 s[4:5], exec
	v_mbcnt_lo_u32_b32 v1, s4, 0
	v_mbcnt_hi_u32_b32 v1, s5, v1
	v_cmp_eq_u32_e32 vcc, 0, v1
	s_and_b64 s[6:7], exec, vcc
	s_mov_b64 exec, s[6:7]
	s_cbranch_execz .LBB0_6
	s_lshl_b32 s3, s91, 8
	s_bcnt1_i32_b64 s4, s[4:5]
	v_mov_b32_e32 v1, s3
	v_mov_b32_e32 v2, s4
	global_atomic_add v1, v2, s[96:97] offset:1024
	s_add_u32 s4, s14, 0xc4000
	s_addc_u32 s5, s15, 0
	s_and_b32 s3, s2, 7
	s_lshl_b32 s3, s3, 8
	v_mov_b32_e32 v1, s3
	s_add_i32 s3, s91, 1
	v_mov_b32_e32 v2, s3
	global_atomic_umax v1, v2, s[4:5]
	s_sub_i32 s3, 16, s91
	v_mov_b32_e32 v3, s3
	global_atomic_umax v1, v3, s[4:5] offset:64

.LBB0_1607:
	s_cmp_gt_i32 s95, 12
	s_cselect_b64 s[0:1], -1, 0
	s_and_b64 s[2:3], s[10:11], s[0:1]
	s_andn2_b64 vcc, exec, s[2:3]
	s_cbranch_vccnz .LBB0_1661
	s_waitcnt vmcnt(0)
	s_waitcnt vmcnt(0)
	s_barrier
	s_mov_b64 s[2:3], exec
	v_readlane_b32 s4, v222, 3
	v_readlane_b32 s5, v222, 4
	s_and_b64 s[4:5], s[2:3], s[4:5]
	s_mov_b64 exec, s[4:5]
	s_cbranch_execz .LBB0_1660
	s_add_u32 s4, s14, 0xc4000
	s_addc_u32 s5, s15, 0
	v_mov_b32_e32 v17, 0
	v_mov_b32_e32 v16, 0
	global_load_dword v1, v17, s[4:5] offset:0 sc1
	global_load_dword v2, v17, s[4:5] offset:64 sc1
	global_load_dword v3, v17, s[4:5] offset:256 sc1
	global_load_dword v4, v17, s[4:5] offset:320 sc1
	s_waitcnt vmcnt(0)
	v_add_u32_e32 v1, v1, v2
	v_add_u32_e32 v3, v3, v4
	v_subrev_u32_e32 v1, 17, v1
	v_subrev_u32_e32 v3, 17, v3
	v_or3_b32 v16, v16, v1, v3
	global_load_dword v1, v17, s[4:5] offset:512 sc1
	global_load_dword v2, v17, s[4:5] offset:576 sc1
	global_load_dword v3, v17, s[4:5] offset:768 sc1
	global_load_dword v4, v17, s[4:5] offset:832 sc1
	s_waitcnt vmcnt(0)
	v_add_u32_e32 v1, v1, v2
	v_add_u32_e32 v3, v3, v4
	v_subrev_u32_e32 v1, 17, v1
	v_subrev_u32_e32 v3, 17, v3
	v_or3_b32 v16, v16, v1, v3
	global_load_dword v1, v17, s[4:5] offset:1024 sc1
	global_load_dword v2, v17, s[4:5] offset:1088 sc1
	global_load_dword v3, v17, s[4:5] offset:1280 sc1
	global_load_dword v4, v17, s[4:5] offset:1344 sc1
	s_waitcnt vmcnt(0)
	v_add_u32_e32 v1, v1, v2
	v_add_u32_e32 v3, v3, v4
	v_subrev_u32_e32 v1, 17, v1
	v_subrev_u32_e32 v3, 17, v3
	v_or3_b32 v16, v16, v1, v3
	global_load_dword v1, v17, s[4:5] offset:1536 sc1
	global_load_dword v2, v17, s[4:5] offset:1600 sc1
	global_load_dword v3, v17, s[4:5] offset:1792 sc1
	global_load_dword v4, v17, s[4:5] offset:1856 sc1
	s_waitcnt vmcnt(0)
	v_add_u32_e32 v1, v1, v2
	v_add_u32_e32 v3, v3, v4
	v_subrev_u32_e32 v1, 17, v1
	v_subrev_u32_e32 v3, 17, v3
	v_or3_b32 v16, v16, v1, v3
	s_nop 0
	v_readfirstlane_b32 s6, v16
	s_cmp_lg_u32 s6, 0
	s_cbranch_scc1 .Lxl_glob_1
	s_lshr_b32 s6, s12, 8
	s_lshl_b32 s6, s6, 8
	s_add_u32 s4, s4, s6
	s_addc_u32 s5, s5, 0
	v_mov_b32_e32 v1, 1
	global_atomic_add v17, v1, s[4:5] offset:128
	s_mov_b32 s6, 0
.Lxl_spin_1:
	global_load_dword v2, v17, s[4:5] offset:128 sc1
	s_waitcnt vmcnt(0)
	v_readfirstlane_b32 s7, v2
	s_cmp_ge_u32 s7, 32
	s_cbranch_scc1 .Lxl_done_1
	s_sleep 1
	s_add_i32 s6, s6, 1
	s_cmp_lt_u32 s6, 0x100000
	s_cbranch_scc1 .Lxl_spin_1
.Lxl_done_1:
	buffer_inv sc1
	s_branch .LBB0_1660
.Lxl_glob_1:
	s_add_i32 s4, 0, 0x23f20
	v_mov_b32_e32 v1, s4
	s_waitcnt vmcnt(0) expcnt(0) lgkmcnt(0)
	ds_read_b32 v3, v1
	s_add_i32 s4, 0, 0x23f24
	v_mov_b32_e32 v1, s4
	ds_read_b32 v1, v1
	s_waitcnt lgkmcnt(1)
	v_cmp_ne_u32_e32 vcc, 0, v3
	s_cbranch_vccnz .LBB0_1624
	v_readlane_b32 s4, v222, 0
	v_readlane_b32 s5, v222, 1
	s_load_dwordx2 s[8:9], s[4:5], 0x4
	s_add_u32 s4, s14, 0x4200
	s_addc_u32 s5, s15, 0
	s_add_u32 s6, s14, 0x4400
	s_addc_u32 s7, s15, 0
	s_waitcnt lgkmcnt(0)
	s_mul_i32 s13, s8, s13
	s_add_u32 s8, s14, 0x4500
	s_mul_i32 s13, s13, s9
	s_addc_u32 s9, s15, 0
	s_add_u32 s10, s14, 0x4600
	s_addc_u32 s11, s15, 0
	s_add_u32 s16, s14, 0x4700
	s_addc_u32 s17, s15, 0
	s_add_u32 s18, s14, 0x4800
	s_addc_u32 s19, s15, 0
	s_add_u32 s20, s14, 0x4900
	s_addc_u32 s21, s15, 0
	s_add_u32 s22, s14, 0x4a00
	s_addc_u32 s23, s15, 0
	s_add_u32 s24, s14, 0x4b00
	s_addc_u32 s25, s15, 0
	s_add_u32 s26, s14, 0x4c00
	s_addc_u32 s27, s15, 0
	s_add_u32 s28, s14, 0x4d00
	s_addc_u32 s29, s15, 0
	s_add_u32 s34, s14, 0x4e00
	s_addc_u32 s35, s15, 0
	s_add_u32 s36, s14, 0x4f00
	s_addc_u32 s37, s15, 0
	s_add_u32 s38, s14, 0x5000
	s_addc_u32 s39, s15, 0
	s_add_u32 s40, s14, 0x5100
	s_addc_u32 s41, s15, 0
	s_add_u32 s42, s14, 0x5200
	s_addc_u32 s43, s15, 0
	s_add_u32 s44, s14, 0x5300
	s_addc_u32 s45, s15, 0
	s_mov_b32 s52, 1
	v_mov_b32_e32 v17, 0
	s_branch .LBB0_1612

.LBB0_1665:
	s_or_b64 exec, exec, s[0:1]
	s_abs_i32 s0, s33
	v_cvt_f32_u32_e32 v1, s0
	s_cmpk_gt_i32 s12, 0x3fff
	s_waitcnt vmcnt(0) lgkmcnt(0)
	s_barrier
	v_rcp_iflag_f32_e32 v1, v1
	s_nop 0
	v_mul_f32_e32 v1, 0x4f7ffffe, v1
	v_cvt_u32_f32_e32 v1, v1
	s_nop 0
	v_readfirstlane_b32 s1, v1
	s_cbranch_scc1 .LBB0_1678
	s_sub_i32 s4, 0, s0
	s_mul_i32 s4, s4, s1
	s_mul_hi_u32 s4, s1, s4
	s_mov_b32 s5, 0
	s_add_i32 s4, s1, s4
	s_lshl_b64 s[4:5], s[4:5], 14
	s_mul_i32 s1, s5, s0
	s_sub_i32 s1, 0x4000, s1
	s_ashr_i32 s6, s33, 31
	s_add_i32 s4, s5, 1
	s_sub_i32 s7, s1, s0
	s_cmp_ge_u32 s1, s0
	v_mbcnt_lo_u32_b32 v1, -1, 0
	s_cselect_b32 s4, s4, s5
	v_mbcnt_hi_u32_b32 v1, -1, v1
	s_cselect_b32 s1, s7, s1
	s_add_i32 s5, s4, 1
	v_and_b32_e32 v2, 64, v1
	s_cmp_ge_u32 s1, s0
	v_add_u32_e32 v2, 64, v2
	v_xor_b32_e32 v3, 1, v1
	s_cselect_b32 s0, s5, s4
	v_cmp_lt_i32_e32 vcc, v3, v2
	s_xor_b32 s0, s0, s6
	s_sub_i32 s0, s0, s6
	v_cndmask_b32_e32 v3, v1, v3, vcc
	v_lshlrev_b32_e32 v158, 2, v3
	v_xor_b32_e32 v3, 2, v1
	s_mul_i32 s1, s0, 5
	v_cmp_lt_i32_e32 vcc, v3, v2
	s_ashr_i32 s4, s1, 31
	s_lshr_b32 s4, s4, 29
	v_cndmask_b32_e32 v3, v1, v3, vcc
	v_lshlrev_b32_e32 v159, 2, v3
	v_xor_b32_e32 v3, 4, v1
	s_add_i32 s1, s1, s4
	v_cmp_lt_i32_e32 vcc, v3, v2
	s_ashr_i32 s19, s1, 3
	s_cmp_lt_i32 s0, 2
	v_cndmask_b32_e32 v3, v1, v3, vcc
	v_lshlrev_b32_e32 v160, 2, v3
	v_xor_b32_e32 v3, 8, v1
	s_cselect_b64 s[4:5], -1, 0
	s_cmp_gt_i32 s0, 1
	v_cmp_lt_i32_e32 vcc, v3, v2
	s_cselect_b64 s[6:7], -1, 0
	s_bfe_u32 s10, s90, 0x30006
	v_cndmask_b32_e32 v3, v1, v3, vcc
	s_lshl_b32 s0, s10, 7
	v_lshlrev_b32_e32 v161, 2, v3
	v_xor_b32_e32 v3, 16, v1
	s_add_u32 s0, s14, s0
	v_cmp_lt_i32_e32 vcc, v3, v2
	s_addc_u32 s1, s15, 0
	v_and_b32_e32 v0, 63, v0
	v_readlane_b32 s14, v222, 6
	v_cndmask_b32_e32 v3, v1, v3, vcc
	v_mov_b32_e32 v17, 0
	v_lshlrev_b32_e32 v16, 3, v0
	v_readlane_b32 s15, v222, 7
	v_lshlrev_b32_e32 v162, 2, v3
	v_xor_b32_e32 v3, 32, v1
	v_lshl_add_u64 v[18:19], s[30:31], 0, v[16:17]
	v_lshl_add_u64 v[20:21], s[14:15], 0, v[16:17]
	v_cmp_lt_i32_e32 vcc, v3, v2
	v_lshlrev_b32_e32 v16, 4, v0
	s_add_u32 s8, s0, 0xba000
	v_cndmask_b32_e32 v1, v1, v3, vcc
	v_lshl_add_u64 v[22:23], s[2:3], 0, v[16:17]
	s_mul_i32 s2, s19, s33
	s_mov_b32 s18, 1
	s_addc_u32 s9, s1, 0
	v_cmp_ne_u32_e64 s[0:1], 0, v0
	v_lshlrev_b32_e32 v163, 2, v1
	v_add_u32_e32 v16, 0, v16
	s_or_b32 s20, s2, s10
	s_add_i32 s21, s12, s33
	s_movk_i32 s22, 0x1000
	v_mov_b32_e32 v164, 0x358637bd
	s_mov_b32 s23, 0xf800000
	v_mov_b32_e32 v165, 0x260
	s_movk_i32 s24, 0x2000
	s_movk_i32 s25, 0x3000
	v_mov_b32_e32 v166, 0
	s_lshr_b32 s99, s12, 8
	s_and_b32 s12, s12, 0xff
	s_lshl_b32 s101, s99, 11
	s_add_i32 s12, s12, s101
	s_add_i32 s21, s12, 0x100
	s_add_i32 s20, s101, 0x500
	s_add_i32 s101, s101, 0x800
	s_lshl_b32 s98, s10, 7
	s_sub_u32 s8, s8, s98
	s_subb_u32 s9, s9, 0
	s_lshl_b32 s98, s99, 7
	s_add_u32 s8, s8, s98
	s_addc_u32 s9, s9, 0
	s_branch .LBB0_1668
.LBB0_1667:
	s_addk_i32 s21, 0x100
	s_add_i32 s18, s18, 1
	s_cmp_lt_i32 s13, s101
	s_mov_b32 s12, s13
	s_cbranch_scc0 .LBB0_1678

.LBB0_1672:
	s_or_b64 exec, exec, s[2:3]
	s_ashr_i32 s13, s12, 31
	s_lshl_b64 s[2:3], s[12:13], 13
	v_lshl_add_u64 v[0:1], v[18:19], 0, s[2:3]
	v_add_co_u32_e32 v12, vcc, 0x1000, v0
	global_load_dwordx2 v[2:3], v[0:1], off offset:512
	global_load_dwordx2 v[4:5], v[0:1], off offset:1024
	global_load_dwordx2 v[6:7], v[0:1], off offset:2048
	global_load_dwordx2 v[8:9], v[0:1], off offset:2560
	global_load_dwordx2 v[10:11], v[0:1], off offset:3072
	v_addc_co_u32_e32 v13, vcc, 0, v1, vcc
	global_load_dwordx2 v[14:15], v[12:13], off
	global_load_dwordx2 v[24:25], v[12:13], off offset:512
	v_lshl_add_u64 v[26:27], v[20:21], 0, s[2:3]
	global_load_dwordx2 v[28:29], v[12:13], off offset:1024
	global_load_dwordx2 v[78:79], v[0:1], off
	global_load_dwordx2 v[106:107], v[0:1], off offset:1536
	global_load_dwordx2 v[112:113], v[0:1], off offset:3584
	global_load_dwordx2 v[76:77], v[26:27], off nt
	global_load_dwordx2 v[86:87], v[26:27], off offset:512 nt
	global_load_dwordx2 v[94:95], v[26:27], off offset:1024 nt
	global_load_dwordx2 v[108:109], v[26:27], off offset:1536 nt
	global_load_dwordx2 v[30:31], v[12:13], off offset:2048
	global_load_dwordx2 v[102:103], v[26:27], off offset:2048 nt
	global_load_dwordx2 v[92:93], v[26:27], off offset:2560 nt
	global_load_dwordx2 v[100:101], v[26:27], off offset:3072 nt
	global_load_dwordx2 v[120:121], v[26:27], off offset:3584 nt
	global_load_dwordx2 v[38:39], v[12:13], off offset:2560
	v_add_co_u32_e32 v0, vcc, s22, v26
	s_lshl_b64 s[2:3], s[12:13], 14
	s_nop 0
	v_addc_co_u32_e32 v1, vcc, 0, v27, vcc
	global_load_dwordx2 v[114:115], v[0:1], off nt
	global_load_dwordx2 v[98:99], v[0:1], off offset:512 nt
	global_load_dwordx2 v[66:67], v[0:1], off offset:1024 nt
	global_load_dwordx2 v[64:65], v[0:1], off offset:1536 nt
	global_load_dwordx2 v[70:71], v[12:13], off offset:3072
	global_load_dwordx2 v[62:63], v[0:1], off offset:2048 nt
	global_load_dwordx2 v[60:61], v[0:1], off offset:2560 nt
	global_load_dwordx2 v[58:59], v[0:1], off offset:3072 nt
	global_load_dwordx2 v[56:57], v[0:1], off offset:3584 nt
	global_load_dwordx2 v[72:73], v[12:13], off offset:1536
	global_load_dwordx2 v[68:69], v[12:13], off offset:3584
	s_waitcnt vmcnt(24)
	v_readfirstlane_b32 s98, v223
	s_nop 1
	v_mov_b32_e32 v166, s98
	v_and_b32_e32 v35, 0xffff0000, v28
	v_lshlrev_b32_e32 v34, 16, v28
	v_and_b32_e32 v33, 0xffff0000, v29
	v_lshlrev_b32_e32 v32, 16, v29
	v_and_b32_e32 v51, 0xffff0000, v3
	v_and_b32_e32 v50, 0xffff0000, v2
	v_lshlrev_b32_e32 v13, 16, v3
	v_lshlrev_b32_e32 v12, 16, v2
	v_pk_mul_f32 v[0:1], v[50:51], v[50:51]
	s_waitcnt vmcnt(16)
	v_lshlrev_b32_e32 v85, 16, v31
	v_pk_fma_f32 v[0:1], v[12:13], v[12:13], v[0:1]
	v_and_b32_e32 v43, 0xffff0000, v15
	v_and_b32_e32 v42, 0xffff0000, v14
	v_lshlrev_b32_e32 v137, 16, v15
	v_lshlrev_b32_e32 v136, 16, v14
	v_pk_add_f32 v[126:127], v[0:1], v[0:1] op_sel:[0,1] op_sel_hi:[1,0]
	v_pk_mul_f32 v[0:1], v[42:43], v[42:43]
	v_and_b32_e32 v41, 0xffff0000, v25
	v_pk_fma_f32 v[0:1], v[136:137], v[136:137], v[0:1]
	v_and_b32_e32 v40, 0xffff0000, v24
	v_pk_add_f32 v[140:141], v[0:1], v[0:1] op_sel:[0,1] op_sel_hi:[1,0]
	v_lshlrev_b32_e32 v169, 16, v25
	v_lshlrev_b32_e32 v168, 16, v24
	v_pk_mul_f32 v[0:1], v[40:41], v[40:41]
	v_lshlrev_b32_e32 v84, 16, v30
	v_pk_fma_f32 v[0:1], v[168:169], v[168:169], v[0:1]
	v_and_b32_e32 v31, 0xffff0000, v31
	v_pk_add_f32 v[156:157], v[0:1], v[0:1] op_sel:[0,1] op_sel_hi:[1,0]
	v_mul_f32_e32 v0, v35, v35
	v_pk_fma_f32 v[152:153], v[34:35], v[34:35], v[0:1] op_sel_hi:[1,1,0]
	v_mul_f32_e32 v0, v33, v33
	v_and_b32_e32 v30, 0xffff0000, v30
	v_pk_fma_f32 v[154:155], v[32:33], v[32:33], v[0:1] op_sel_hi:[1,1,0]
	v_pk_mul_f32 v[0:1], v[30:31], v[30:31]
	v_and_b32_e32 v37, 0xffff0000, v11
	v_pk_fma_f32 v[0:1], v[84:85], v[84:85], v[0:1]
	s_waitcnt vmcnt(11)
	v_and_b32_e32 v29, 0xffff0000, v39
	v_and_b32_e32 v28, 0xffff0000, v38
	v_lshlrev_b32_e32 v36, 16, v11
	v_mul_f32_e32 v26, v37, v37
	v_pk_add_f32 v[146:147], v[0:1], v[0:1] op_sel:[0,1] op_sel_hi:[1,0]
	v_lshlrev_b32_e32 v83, 16, v39
	v_lshlrev_b32_e32 v82, 16, v38
	v_pk_mul_f32 v[0:1], v[28:29], v[28:29]
	v_pk_fma_f32 v[130:131], v[36:37], v[36:37], v[26:27] op_sel_hi:[1,1,0]
	v_pk_fma_f32 v[0:1], v[82:83], v[82:83], v[0:1]
	s_waitcnt vmcnt(6)
	v_and_b32_e32 v27, 0xffff0000, v70
	v_pk_add_f32 v[150:151], v[0:1], v[0:1] op_sel:[0,1] op_sel_hi:[1,0]
	v_lshlrev_b32_e32 v26, 16, v70
	v_mul_f32_e32 v0, v27, v27
	v_and_b32_e32 v25, 0xffff0000, v71
	v_pk_fma_f32 v[144:145], v[26:27], v[26:27], v[0:1] op_sel_hi:[1,1,0]
	v_lshlrev_b32_e32 v24, 16, v71
	v_mul_f32_e32 v0, v25, v25
	v_and_b32_e32 v75, 0xffff0000, v78
	v_pk_fma_f32 v[148:149], v[24:25], v[24:25], v[0:1] op_sel_hi:[1,1,0]
	v_lshlrev_b32_e32 v74, 16, v78
	v_mul_f32_e32 v0, v75, v75
	v_lshlrev_b32_e32 v78, 16, v79
	v_and_b32_e32 v79, 0xffff0000, v79
	v_pk_fma_f32 v[128:129], v[74:75], v[74:75], v[0:1] op_sel_hi:[1,1,0]
	v_mul_f32_e32 v0, v79, v79
	v_and_b32_e32 v53, 0xffff0000, v4
	v_and_b32_e32 v55, 0xffff0000, v5
	v_pk_fma_f32 v[134:135], v[78:79], v[78:79], v[0:1] op_sel_hi:[1,1,0]
	v_lshlrev_b32_e32 v52, 16, v4
	v_lshlrev_b32_e32 v54, 16, v5
	v_mul_f32_e32 v2, v53, v53
	v_mul_f32_e32 v4, v55, v55
	v_and_b32_e32 v143, 0xffff0000, v106
	v_and_b32_e32 v142, s0, v106
	v_pk_add_f32 v[128:129], v[128:129], v[134:135]
	v_lshlrev_b32_e32 v134, 16, v107
	v_and_b32_e32 v135, 0xffff0000, v107
	v_pk_fma_f32 v[110:111], v[52:53], v[52:53], v[2:3] op_sel_hi:[1,1,0]
	v_pk_fma_f32 v[118:119], v[54:55], v[54:55], v[4:5] op_sel_hi:[1,1,0]
	v_lshlrev_b32_e32 v104, 16, v106
	v_mov_b32_e32 v105, v143
	v_pk_mul_f32 v[142:143], v[142:143], v[142:143]
	v_pk_mul_f32 v[106:107], v[134:135], v[134:135]
	v_and_b32_e32 v49, 0xffff0000, v7
	v_and_b32_e32 v48, 0xffff0000, v6
	v_mul_f32_e32 v129, v104, v104
	v_mov_b32_e32 v127, v143
	v_mov_b32_e32 v111, v106
	v_mov_b32_e32 v119, v107
	v_lshlrev_b32_e32 v117, 16, v7
	v_lshlrev_b32_e32 v116, 16, v6
	v_and_b32_e32 v47, 0xffff0000, v9
	v_and_b32_e32 v46, 0xffff0000, v8
	v_pk_mul_f32 v[6:7], v[48:49], v[48:49]
	v_pk_add_f32 v[126:127], v[128:129], v[126:127]
	v_pk_add_f32 v[106:107], v[110:111], v[118:119]
	v_lshlrev_b32_e32 v123, 16, v9
	v_lshlrev_b32_e32 v122, 16, v8
	v_pk_mul_f32 v[8:9], v[46:47], v[46:47]
	v_pk_fma_f32 v[2:3], v[116:117], v[116:117], v[6:7]
	v_pk_add_f32 v[106:107], v[126:127], v[106:107]
	v_pk_fma_f32 v[4:5], v[122:123], v[122:123], v[8:9]
	v_pk_add_f32 v[132:133], v[2:3], v[2:3] op_sel:[0,1] op_sel_hi:[1,0]
	v_pk_add_f32 v[170:171], v[106:107], v[106:107] op_sel:[0,1] op_sel_hi:[1,0]
	v_lshlrev_b32_e32 v106, 16, v112
	v_and_b32_e32 v107, 0xffff0000, v112
	v_pk_add_f32 v[138:139], v[4:5], v[4:5] op_sel:[0,1] op_sel_hi:[1,0]
	v_mov_b32_e32 v126, v122
	v_mov_b32_e32 v127, v46
	v_mov_b32_e32 v46, v123
	v_pk_mul_f32 v[122:123], v[106:107], v[106:107]
	v_pk_add_f32 v[132:133], v[170:171], v[132:133]
	v_and_b32_e32 v45, 0xffff0000, v10
	v_mov_b32_e32 v139, v123
	v_mov_b32_e32 v133, v122
	v_lshlrev_b32_e32 v44, 16, v10
	v_mul_f32_e32 v10, v45, v45
	v_pk_add_f32 v[138:139], v[132:133], v[138:139]
	v_lshlrev_b32_e32 v132, 16, v113
	v_and_b32_e32 v133, 0xffff0000, v113
	v_pk_fma_f32 v[124:125], v[44:45], v[44:45], v[10:11] op_sel_hi:[1,1,0]
	v_pk_mul_f32 v[112:113], v[132:133], v[132:133]
	v_lshl_add_u64 v[38:39], v[22:23], 0, s[2:3]
	v_mov_b32_e32 v125, v112
	v_mov_b32_e32 v131, v113
	v_pk_add_f32 v[112:113], v[124:125], v[130:131]
	v_lshlrev_b32_e32 v124, 16, v115
	v_pk_add_f32 v[112:113], v[138:139], v[112:113]
	v_and_b32_e32 v125, 0xffff0000, v115
	v_pk_add_f32 v[170:171], v[112:113], v[112:113] op_sel:[0,1] op_sel_hi:[1,0]
	v_lshlrev_b32_e32 v112, 16, v114
	v_and_b32_e32 v113, 0xffff0000, v114
	s_waitcnt vmcnt(1)
	v_lshlrev_b32_e32 v114, 16, v72
	v_and_b32_e32 v115, 0xffff0000, v72
	v_mov_b32_e32 v138, v136
	v_mov_b32_e32 v139, v42
	v_mov_b32_e32 v42, v137
	v_mov_b32_e32 v136, v168
	v_mov_b32_e32 v137, v40
	v_mov_b32_e32 v40, v169
	v_pk_mul_f32 v[168:169], v[114:115], v[114:115]
	v_pk_add_f32 v[140:141], v[170:171], v[140:141]
	v_mov_b32_e32 v157, v169
	v_mov_b32_e32 v141, v168
	v_pk_add_f32 v[156:157], v[140:141], v[156:157]
	v_lshlrev_b32_e32 v140, 16, v73
	v_and_b32_e32 v141, 0xffff0000, v73
	v_pk_mul_f32 v[72:73], v[140:141], v[140:141]
	ds_read_b128 v[4:7], v16
	ds_read_b128 v[0:3], v16 offset:1024
	v_mov_b32_e32 v153, v72
	v_mov_b32_e32 v155, v73
	v_pk_add_f32 v[72:73], v[152:153], v[154:155]
	s_waitcnt vmcnt(0)
	v_and_b32_e32 v155, 0xffff0000, v68
	v_pk_add_f32 v[72:73], v[156:157], v[72:73]
	v_and_b32_e32 v154, s0, v68
	v_pk_add_f32 v[152:153], v[72:73], v[72:73] op_sel:[0,1] op_sel_hi:[1,0]
	v_lshlrev_b32_e32 v72, 16, v68
	v_pk_mul_f32 v[156:157], v[154:155], v[154:155]
	v_pk_add_f32 v[146:147], v[152:153], v[146:147]
	v_mov_b32_e32 v151, v157
	v_mul_f32_e32 v147, v72, v72
	v_lshlrev_b32_e32 v68, 16, v69
	v_and_b32_e32 v69, 0xffff0000, v69
	v_pk_add_f32 v[146:147], v[146:147], v[150:151]
	v_pk_mul_f32 v[150:151], v[68:69], v[68:69]
	v_lshlrev_b32_e32 v70, 16, v76
	v_mov_b32_e32 v145, v150
	v_mov_b32_e32 v149, v151
	v_pk_add_f32 v[144:145], v[144:145], v[148:149]
	v_mov_b32_e32 v148, v84
	v_pk_add_f32 v[144:145], v[146:147], v[144:145]
	v_mov_b32_e32 v149, v30
	v_add_f32_e32 v73, v144, v145
	ds_bpermute_b32 v145, v158, v73
	v_mov_b32_e32 v30, v85
	v_lshlrev_b32_e32 v84, 16, v60
	v_and_b32_e32 v85, 0xffff0000, v60
	v_mov_b32_e32 v151, v28
	s_waitcnt lgkmcnt(0)
	v_add_f32_e32 v73, v73, v145
	ds_bpermute_b32 v147, v159, v73
	v_mov_b32_e32 v28, v83
	v_and_b32_e32 v83, 0xffff0000, v56
	v_and_b32_e32 v71, 0xffff0000, v76
	v_lshlrev_b32_e32 v76, 16, v77
	s_waitcnt lgkmcnt(0)
	v_add_f32_e32 v73, v73, v147
	ds_bpermute_b32 v150, v160, v73
	v_and_b32_e32 v77, 0xffff0000, v77
	v_mov_b32_e32 v88, v12
	v_mov_b32_e32 v89, v50
	v_lshlrev_b32_e32 v80, 16, v86
	s_waitcnt lgkmcnt(0)
	v_add_f32_e32 v73, v73, v150
	ds_bpermute_b32 v150, v161, v73
	v_and_b32_e32 v81, 0xffff0000, v86
	v_mov_b32_e32 v50, v13
	ds_read_b128 v[12:15], v16 offset:2048
	ds_read_b128 v[8:11], v16 offset:3072
	v_lshlrev_b32_e32 v86, 16, v87
	s_waitcnt lgkmcnt(2)
	v_add_f32_e32 v60, v73, v150
	ds_bpermute_b32 v73, v162, v60
	v_mov_b32_e32 v150, v82
	v_and_b32_e32 v87, 0xffff0000, v87
	v_lshlrev_b32_e32 v90, 16, v94
	v_and_b32_e32 v91, 0xffff0000, v94
	s_waitcnt lgkmcnt(0)
	v_add_f32_e32 v73, v60, v73
	ds_bpermute_b32 v82, v163, v73
	v_lshlrev_b32_e32 v94, 16, v95
	v_and_b32_e32 v95, 0xffff0000, v95
	v_lshlrev_b32_e32 v96, 16, v108
	v_and_b32_e32 v97, 0xffff0000, v108
	s_waitcnt lgkmcnt(0)
	v_add_f32_e32 v73, v73, v82
	v_fmamk_f32 v73, v73, 0x39800000, v164
	v_mul_f32_e32 v82, 0x4f800000, v73
	v_cmp_gt_f32_e32 vcc, s23, v73
	v_lshlrev_b32_e32 v128, 16, v109
	v_and_b32_e32 v129, 0xffff0000, v109
	v_cndmask_b32_e32 v73, v73, v82, vcc
	v_sqrt_f32_e32 v154, v73
	v_lshlrev_b32_e32 v82, 16, v56
	v_lshlrev_b32_e32 v110, 16, v102
	v_and_b32_e32 v111, 0xffff0000, v102
	v_add_u32_e32 v56, -1, v154
	v_fma_f32 v156, -v56, v154, v73
	v_cmp_ge_f32_e64 s[2:3], 0, v156
	v_add_u32_e32 v156, 1, v154
	v_mov_b32_e32 v142, v116
	v_cndmask_b32_e64 v56, v154, v56, s[2:3]
	v_fma_f32 v154, -v156, v154, v73
	v_cmp_lt_f32_e64 s[2:3], 0, v154
	v_mov_b32_e32 v143, v48
	v_lshlrev_b32_e32 v118, 16, v103
	v_cndmask_b32_e64 v56, v56, v156, s[2:3]
	v_mul_f32_e32 v154, 0x37800000, v56
	v_cndmask_b32_e32 v56, v56, v154, vcc
	v_cmp_class_f32_e32 vcc, v73, v165
	v_and_b32_e32 v119, 0xffff0000, v103
	v_mov_b32_e32 v48, v117
	v_cndmask_b32_e32 v154, v56, v73, vcc
	v_div_scale_f32 v156, s[2:3], v154, v154, 0.5
	v_rcp_f32_e32 v157, v156
	v_mov_b32_e32 v73, v155
	v_lshlrev_b32_e32 v116, 16, v92
	v_and_b32_e32 v117, 0xffff0000, v92
	v_fma_f32 v155, -v156, v157, 1.0
	v_fmac_f32_e32 v157, v155, v157
	v_div_scale_f32 v155, vcc, 0.5, v154, 0.5
	v_mul_f32_e32 v167, v155, v157
	v_fma_f32 v168, -v156, v167, v155
	v_fmac_f32_e32 v167, v168, v157
	v_fma_f32 v155, -v156, v167, v155
	v_div_fmas_f32 v155, v155, v157, v167
	v_div_fixup_f32 v154, v155, v154, 0.5
	v_pk_mul_f32 v[74:75], v[154:155], v[74:75] op_sel_hi:[0,1]
	v_pk_fma_f32 v[4:5], v[4:5], v[74:75], v[70:71]
	v_pk_mul_f32 v[70:71], v[154:155], v[78:79] op_sel_hi:[0,1]
	v_pk_fma_f32 v[6:7], v[6:7], v[70:71], v[76:77]
	global_store_dwordx4 v[38:39], v[4:7], off nt
	v_lshlrev_b32_e32 v108, 16, v93
	v_and_b32_e32 v109, 0xffff0000, v93
	v_pk_mul_f32 v[4:5], v[154:155], v[88:89] op_sel_hi:[0,1]
	v_pk_fma_f32 v[0:1], v[0:1], v[4:5], v[80:81]
	v_pk_mul_f32 v[4:5], v[154:155], v[50:51] op_sel_hi:[0,1]
	v_pk_fma_f32 v[2:3], v[2:3], v[4:5], v[86:87]
	global_store_dwordx4 v[38:39], v[0:3], off offset:1024 nt
	v_lshlrev_b32_e32 v92, 16, v100
	v_and_b32_e32 v93, 0xffff0000, v100
	v_pk_mul_f32 v[0:1], v[154:155], v[52:53] op_sel_hi:[0,1]
	v_pk_mul_f32 v[2:3], v[154:155], v[54:55] op_sel_hi:[0,1]
	v_pk_fma_f32 v[0:1], v[12:13], v[0:1], v[90:91]
	v_pk_fma_f32 v[2:3], v[14:15], v[2:3], v[94:95]
	global_store_dwordx4 v[38:39], v[0:3], off offset:2048 nt
	v_lshlrev_b32_e32 v100, 16, v101
	v_and_b32_e32 v101, 0xffff0000, v101
	v_pk_mul_f32 v[0:1], v[154:155], v[104:105] op_sel_hi:[0,1]
	v_pk_mul_f32 v[2:3], v[154:155], v[134:135] op_sel_hi:[0,1]
	v_pk_fma_f32 v[0:1], v[0:1], v[8:9], v[96:97]
	v_pk_fma_f32 v[2:3], v[2:3], v[10:11], v[128:129]
	v_lshlrev_b32_e32 v102, 16, v120
	v_and_b32_e32 v103, 0xffff0000, v120
	v_lshlrev_b32_e32 v122, 16, v121
	v_and_b32_e32 v123, 0xffff0000, v121
	v_lshlrev_b32_e32 v130, 16, v98
	v_and_b32_e32 v131, 0xffff0000, v98
	v_lshlrev_b32_e32 v120, 16, v99
	v_and_b32_e32 v121, 0xffff0000, v99
	v_lshlrev_b32_e32 v98, 16, v66
	v_and_b32_e32 v99, 0xffff0000, v66
	v_lshlrev_b32_e32 v66, 16, v67
	v_and_b32_e32 v67, 0xffff0000, v67
	v_lshlrev_b32_e32 v144, 16, v64
	v_and_b32_e32 v145, 0xffff0000, v64
	v_lshlrev_b32_e32 v64, 16, v65
	v_and_b32_e32 v65, 0xffff0000, v65
	v_lshlrev_b32_e32 v146, 16, v62
	v_and_b32_e32 v147, 0xffff0000, v62
	v_lshlrev_b32_e32 v62, 16, v63
	v_and_b32_e32 v63, 0xffff0000, v63
	v_lshlrev_b32_e32 v152, 16, v61
	v_and_b32_e32 v153, 0xffff0000, v61
	v_lshlrev_b32_e32 v60, 16, v58
	v_and_b32_e32 v61, 0xffff0000, v58
	v_lshlrev_b32_e32 v58, 16, v59
	v_and_b32_e32 v59, 0xffff0000, v59
	v_lshlrev_b32_e32 v56, 16, v57
	v_and_b32_e32 v57, 0xffff0000, v57
	global_store_dwordx4 v[38:39], v[0:3], off offset:3072 nt
	ds_read_b128 v[0:3], v16 offset:4096
	ds_read_b128 v[4:7], v16 offset:5120
	v_add_co_u32_e32 v12, vcc, s22, v38
	v_pk_mul_f32 v[8:9], v[154:155], v[142:143] op_sel_hi:[0,1]
	s_nop 0
	v_addc_co_u32_e32 v13, vcc, 0, v39, vcc
	v_pk_mul_f32 v[10:11], v[154:155], v[48:49] op_sel_hi:[0,1]
	v_add_co_u32_e32 v14, vcc, s24, v38
	s_waitcnt lgkmcnt(1)
	v_pk_fma_f32 v[0:1], v[8:9], v[0:1], v[110:111]
	v_pk_fma_f32 v[2:3], v[10:11], v[2:3], v[118:119]
	v_addc_co_u32_e32 v15, vcc, 0, v39, vcc
	global_store_dwordx4 v[14:15], v[0:3], off offset:-4096 nt
	ds_read_b128 v[8:11], v16 offset:6144
	s_nop 0
	v_pk_mul_f32 v[0:1], v[154:155], v[126:127] op_sel_hi:[0,1]
	v_pk_mul_f32 v[2:3], v[154:155], v[46:47] op_sel_hi:[0,1]
	s_waitcnt lgkmcnt(1)
	v_pk_fma_f32 v[0:1], v[0:1], v[4:5], v[116:117]
	v_pk_fma_f32 v[2:3], v[2:3], v[6:7], v[108:109]
	global_store_dwordx4 v[12:13], v[0:3], off offset:1024 nt
	ds_read_b128 v[0:3], v16 offset:7168
	v_pk_mul_f32 v[4:5], v[154:155], v[44:45] op_sel_hi:[0,1]
	v_pk_mul_f32 v[6:7], v[154:155], v[36:37] op_sel_hi:[0,1]
	s_waitcnt lgkmcnt(1)
	v_pk_fma_f32 v[4:5], v[4:5], v[8:9], v[92:93]
	v_pk_fma_f32 v[6:7], v[6:7], v[10:11], v[100:101]
	global_store_dwordx4 v[12:13], v[4:7], off offset:2048 nt
	s_nop 1
	v_pk_mul_f32 v[4:5], v[154:155], v[106:107] op_sel_hi:[0,1]
	s_waitcnt lgkmcnt(0)
	v_pk_fma_f32 v[0:1], v[4:5], v[0:1], v[102:103]
	v_pk_mul_f32 v[4:5], v[154:155], v[132:133] op_sel_hi:[0,1]
	v_pk_fma_f32 v[2:3], v[4:5], v[2:3], v[122:123]
	global_store_dwordx4 v[12:13], v[0:3], off offset:3072 nt
	ds_read_b128 v[0:3], v16 offset:8192
	ds_read_b128 v[4:7], v16 offset:9216
	v_pk_mul_f32 v[8:9], v[154:155], v[138:139] op_sel_hi:[0,1]
	v_pk_mul_f32 v[10:11], v[154:155], v[42:43] op_sel_hi:[0,1]
	s_waitcnt lgkmcnt(1)
	v_pk_fma_f32 v[0:1], v[8:9], v[0:1], v[112:113]
	v_pk_fma_f32 v[2:3], v[10:11], v[2:3], v[124:125]
	global_store_dwordx4 v[14:15], v[0:3], off nt
	ds_read_b128 v[8:11], v16 offset:10240
	s_nop 0
	v_pk_mul_f32 v[0:1], v[154:155], v[136:137] op_sel_hi:[0,1]
	v_pk_mul_f32 v[2:3], v[154:155], v[40:41] op_sel_hi:[0,1]
	s_waitcnt lgkmcnt(1)
	v_pk_fma_f32 v[0:1], v[0:1], v[4:5], v[130:131]
	v_pk_fma_f32 v[2:3], v[2:3], v[6:7], v[120:121]
	global_store_dwordx4 v[14:15], v[0:3], off offset:1024 nt
	ds_read_b128 v[0:3], v16 offset:11264
	v_pk_mul_f32 v[4:5], v[154:155], v[34:35] op_sel_hi:[0,1]
	v_pk_mul_f32 v[6:7], v[154:155], v[32:33] op_sel_hi:[0,1]
	s_waitcnt lgkmcnt(1)
	v_pk_fma_f32 v[4:5], v[4:5], v[8:9], v[98:99]
	v_pk_fma_f32 v[6:7], v[6:7], v[10:11], v[66:67]
	global_store_dwordx4 v[14:15], v[4:7], off offset:2048 nt
	s_nop 1
	v_pk_mul_f32 v[4:5], v[154:155], v[114:115] op_sel_hi:[0,1]
	s_waitcnt lgkmcnt(0)
	v_pk_fma_f32 v[0:1], v[4:5], v[0:1], v[144:145]
	v_pk_mul_f32 v[4:5], v[154:155], v[140:141] op_sel_hi:[0,1]
	v_pk_fma_f32 v[2:3], v[4:5], v[2:3], v[64:65]
	global_store_dwordx4 v[14:15], v[0:3], off offset:3072 nt
	ds_read_b128 v[0:3], v16 offset:12288
	ds_read_b128 v[4:7], v16 offset:13312
	v_pk_mul_f32 v[8:9], v[154:155], v[148:149] op_sel_hi:[0,1]
	v_pk_mul_f32 v[10:11], v[154:155], v[30:31] op_sel_hi:[0,1]
	v_add_co_u32_e32 v12, vcc, s25, v38
	s_waitcnt lgkmcnt(1)
	v_pk_fma_f32 v[0:1], v[8:9], v[0:1], v[146:147]
	v_pk_fma_f32 v[2:3], v[10:11], v[2:3], v[62:63]
	v_addc_co_u32_e32 v13, vcc, 0, v39, vcc
	global_store_dwordx4 v[12:13], v[0:3], off nt
	ds_read_b128 v[8:11], v16 offset:14336
	s_nop 0
	v_pk_mul_f32 v[0:1], v[154:155], v[150:151] op_sel_hi:[0,1]
	v_pk_mul_f32 v[2:3], v[154:155], v[28:29] op_sel_hi:[0,1]
	s_waitcnt lgkmcnt(1)
	v_pk_fma_f32 v[0:1], v[0:1], v[4:5], v[84:85]
	v_pk_fma_f32 v[2:3], v[2:3], v[6:7], v[152:153]
	global_store_dwordx4 v[12:13], v[0:3], off offset:1024 nt
	ds_read_b128 v[0:3], v16 offset:15360
	v_pk_mul_f32 v[4:5], v[154:155], v[26:27] op_sel_hi:[0,1]
	v_pk_mul_f32 v[6:7], v[154:155], v[24:25] op_sel_hi:[0,1]
	s_waitcnt lgkmcnt(1)
	v_pk_fma_f32 v[4:5], v[4:5], v[8:9], v[60:61]
	v_pk_fma_f32 v[6:7], v[6:7], v[10:11], v[58:59]
	global_store_dwordx4 v[12:13], v[4:7], off offset:2048 nt
	s_nop 1
	v_pk_mul_f32 v[4:5], v[154:155], v[72:73] op_sel_hi:[0,1]
	s_waitcnt lgkmcnt(0)
	v_pk_fma_f32 v[0:1], v[4:5], v[0:1], v[82:83]
	v_pk_mul_f32 v[4:5], v[154:155], v[68:69] op_sel_hi:[0,1]
	v_pk_fma_f32 v[2:3], v[4:5], v[2:3], v[56:57]
	global_store_dwordx4 v[12:13], v[0:3], off offset:3072 nt
	s_mov_b64 s[2:3], -1
	s_and_b64 vcc, exec, s[6:7]
	s_cbranch_vccz .LBB0_1676
	s_andn2_b64 vcc, exec, s[10:11]
	s_mov_b32 s13, s21
	s_cbranch_vccnz .LBB0_1675
	v_readfirstlane_b32 s2, v166
	s_nop 0
	s_add_i32 s13, s20, s2
